# speedup vs baseline: 1.0070x; 1.0070x over previous
; #define LAS __attribute__((address_space(3)))
; __device__ __forceinline__ void rw_scan4(const int tid, LAS float* lds, const float* RW, int task, int ntasks, int mode, const float* SIN, float* PQ, float* Y) {
;     const int slot = tid >> 7, sl = tid & 127, kp = sl & 7, rg = sl >> 3;
;     const bool active = task < ntasks;
;     int head = 0, c = 0, kind = 2;
;     if (active) { if (mode == 0) { kind = task & 1; head = (task >> 1) & 7; c = task >> 4; } else { head = task & 7; c = task >> 3; } }
;     const int t0 = c * CHL;
;     f32x2 s[4][4];
;     if (kind == 2 && active) {
;         const float* ip = SIN + (size_t)(head * NCH + c) * 4096 + (rg * 4) * 64 + kp * 8;
; #pragma unroll
;         for (int j = 0; j < 4; ++j) { const f32x4 i0 = *(const f32x4*)(ip + j * 64), i1 = *(const f32x4*)(ip + j * 64 + 4);
;             s[j][0] = (f32x2){i0.x, i0.y}; s[j][1] = (f32x2){i0.z, i0.w}; s[j][2] = (f32x2){i1.x, i1.y}; s[j][3] = (f32x2){i1.z, i1.w}; }
;     } else {
; #pragma unroll
;         for (int j = 0; j < 4; ++j)
; #pragma unroll
;             for (int i = 0; i < 4; ++i) { const int kk = kp * 8 + 2 * i, rr = rg * 4 + j; s[j][i] = (f32x2){(kind == 1 && kk == rr) ? 1.f : 0.f, (kind == 1 && kk + 1 == rr) ? 1.f : 0.f}; }
;     }
;     LAS float* sb = lds + slot * (2 * 6 * TB * 64);
;     const int srow = sl >> 4, sc4 = sl & 15;
;     const float* gsrc = RW + (size_t)(t0 + srow) * GW + head * 64 + sc4 * 4;
;     f32x4 st[6];
.LBB0_210:
	v_readlane_b32 s0, v254, 29
	s_cmp_gt_i32 s0, 4
	s_mov_b64 s[0:1], -1
	s_cbranch_scc0 .LBB0_347
	v_readlane_b32 s0, v254, 29
	s_cmp_gt_i32 s0, 5
	s_mov_b64 s[0:1], -1
	s_cbranch_scc0 .LBB0_314
	s_waitcnt vmcnt(5)
	v_and_b32_e32 v1, 7, v148
	s_waitcnt vmcnt(4)
	v_bfe_u32 v6, v148, 3, 4
	v_ashrrev_i32_e32 v0, 7, v148
	v_lshlrev_b32_e32 v2, 3, v1
	v_lshlrev_b32_e32 v3, 2, v6
	s_movk_i32 s4, 0x6000
	v_lshlrev_b32_e32 v130, 2, v148
	v_and_b32_e32 v131, 1, v0
	v_lshrrev_b32_e32 v132, 1, v0
	v_lshlrev_b32_e32 v131, 1, v131
	v_or_b32_e32 v131, v131, v132
	v_lshl_add_u32 v131, s44, 2, v131
	v_cmp_eq_u32_e64 s[38:39], v2, v3
	v_or_b32_e32 v2, 4, v2
	v_mul_lo_u32 v7, v0, s4
	v_bfe_u32 v133, v148, 4, 3
	v_and_b32_e32 v0, 60, v130
	v_readlane_b32 s0, v254, 32
	v_cmp_eq_u32_e64 s[40:41], v2, v3
	v_add_u32_e32 v3, 0, v7
	v_lshlrev_b32_e32 v4, 2, v0
	v_lshlrev_b32_e32 v2, 5, v1
	v_lshlrev_b32_e32 v1, 8, v133
	v_readlane_b32 s1, v254, 33
	v_add3_u32 v134, v3, v4, v1
	v_lshlrev_b32_e32 v4, 10, v6
	v_mov_b32_e32 v5, v144
	s_load_dwordx16 s[48:63], s[0:1], 0x38
	s_waitcnt lgkmcnt(0)
	v_lshl_add_u64 v[4:5], s[18:19], 0, v[4:5]
	v_mov_b32_e32 v3, v144
	v_lshl_add_u64 v[4:5], v[4:5], 0, v[2:3]
	s_mov_b64 s[4:5], 0x28300000
	s_add_u32 s0, s18, 0x16200000
	v_lshl_add_u64 v[92:93], v[4:5], 0, s[4:5]
	v_lshl_or_b32 v1, v6, 4, v7
	v_readlane_b32 s4, v254, 15
	s_addc_u32 s1, s19, 0
	s_lshl_b32 s14, s45, 2
	v_add_u32_e32 v135, s4, v1
	v_or_b32_e32 v1, v7, v2
	s_add_i32 s4, 0, 0x800
	v_cmp_eq_u32_e64 s[42:43], 1, v132
	v_add_u32_e32 v136, s4, v1
	s_mov_b32 s15, 0
	v_lshlrev_b32_e32 v94, 2, v0
	s_branch .LBB0_214
